# gemm1 epilogue natural-layout staged store: 8 LDS reads batched with offset immediates, global address stepped by a precomputed stride instead of 8 x 64-bit multiplies
# baseline (speedup 1.0000x reference)
; __device__ __forceinline__ void phase_gemm1(PREF P, int slab, char* smem) {
;     ...
;     if (nbuf) {
; #pragma unroll
;       for (int i = 0; i < 4; ++i)
; #pragma unroll
;         for (int j = 0; j < 4; ++j) {
;           const int rl = wm * 64 + i * 16 + l15, cl = (j & 1) * 16 + wn * 32 + (j >> 1) * 64 + q * 4;
;           u32x2 o; o.x = pack2(acc[i][j][0], acc[i][j][1]); o.y = pack2(acc[i][j][2], acc[i][j][3]);
;           *(u32x2*)(smem + rl * 272 + cl * 2) = o;
;         }
;       __syncthreads();
; #pragma unroll
;       for (int k = 0; k < 8; ++k) {
;         const int chunk = tid + 256 * k, rl = chunk >> 4, c16 = chunk & 15;
;         u32x4 d = *(const u32x4*)(smem + rl * 272 + c16 * 16);
;         __builtin_nontemporal_store(d, (u32x4*)(nbuf + (size_t)(m0 + rl) * nld + ncol + c16 * 8));
;       }
.LBB0_765:
	v_cvt_pk_bf16_f32 v68, v60, v61
	v_cvt_pk_bf16_f32 v69, v62, v63
	v_cvt_pk_bf16_f32 v72, v56, v57
	v_cvt_pk_bf16_f32 v73, v58, v59
	ds_write2_b64 v97, v[68:69], v[72:73] offset1:4
	v_cvt_pk_bf16_f32 v68, v52, v53
	v_cvt_pk_bf16_f32 v69, v54, v55
	v_cvt_pk_bf16_f32 v72, v48, v49
	v_cvt_pk_bf16_f32 v73, v50, v51
	ds_write2_b64 v97, v[68:69], v[72:73] offset0:16 offset1:20
	v_cvt_pk_bf16_f32 v68, v44, v45
	v_cvt_pk_bf16_f32 v69, v46, v47
	v_cvt_pk_bf16_f32 v72, v40, v41
	v_cvt_pk_bf16_f32 v73, v42, v43
	v_add_u32_e32 v71, 0x1000, v97
	ds_write2_b64 v71, v[68:69], v[72:73] offset0:32 offset1:36
	v_cvt_pk_bf16_f32 v68, v36, v37
	v_cvt_pk_bf16_f32 v69, v38, v39
	v_cvt_pk_bf16_f32 v72, v32, v33
	v_cvt_pk_bf16_f32 v73, v34, v35
	ds_write2_b64 v71, v[68:69], v[72:73] offset0:48 offset1:52
	v_cvt_pk_bf16_f32 v68, v28, v29
	v_cvt_pk_bf16_f32 v69, v30, v31
	v_cvt_pk_bf16_f32 v72, v24, v25
	v_cvt_pk_bf16_f32 v73, v26, v27
	v_add_u32_e32 v71, 0x2000, v97
	ds_write2_b64 v71, v[68:69], v[72:73] offset0:64 offset1:68
	v_cvt_pk_bf16_f32 v68, v20, v21
	v_cvt_pk_bf16_f32 v69, v22, v23
	v_cvt_pk_bf16_f32 v72, v16, v17
	v_cvt_pk_bf16_f32 v73, v18, v19
	ds_write2_b64 v71, v[68:69], v[72:73] offset0:80 offset1:84
	v_cvt_pk_bf16_f32 v68, v12, v13
	v_cvt_pk_bf16_f32 v69, v14, v15
	v_cvt_pk_bf16_f32 v72, v8, v9
	v_cvt_pk_bf16_f32 v73, v10, v11
	v_add_u32_e32 v71, 0x3000, v97
	ds_write2_b64 v71, v[68:69], v[72:73] offset0:96 offset1:100
	v_cvt_pk_bf16_f32 v68, v4, v5
	v_cvt_pk_bf16_f32 v69, v6, v7
	v_cvt_pk_bf16_f32 v72, v0, v1
	v_cvt_pk_bf16_f32 v73, v2, v3
	ds_write2_b64 v71, v[68:69], v[72:73] offset0:112 offset1:116
	v_lshlrev_b32_e32 v68, 4, v70
	v_and_b32_e32 v180, 0xf0, v68
	v_ashrrev_i32_e32 v71, 4, v70
	v_mad_u64_u32 v[68:69], s[16:17], v71, s11, v[180:181]
	s_waitcnt lgkmcnt(0)
	s_barrier
	ds_read_b128 v[72:75], v68
	ds_read_b128 v[224:227], v68 offset:4352
	ds_read_b128 v[228:231], v68 offset:8704
	ds_read_b128 v[232:235], v68 offset:13056
	ds_read_b128 v[236:239], v68 offset:17408
	ds_read_b128 v[240:243], v68 offset:21760
	ds_read_b128 v[244:247], v68 offset:26112
	ds_read_b128 v[100:103], v68 offset:30464
	v_add_u32_e32 v68, s36, v71
	s_ashr_i32 s45, s44, 31
	v_ashrrev_i32_e32 v69, 31, v68
	v_lshl_add_u64 v[64:65], s[44:45], 1, v[64:65]
	v_mul_lo_u32 v71, s42, v69
	v_mul_lo_u32 v76, s43, v68
	v_mad_u64_u32 v[68:69], s[16:17], s42, v68, 0
	v_lshl_add_u64 v[64:65], v[64:65], 0, v[180:181]
	v_add3_u32 v69, v69, v71, v76
	v_lshl_add_u64 v[68:69], v[68:69], 1, v[64:65]
	v_lshlrev_b64 v[186:187], 5, s[42:43]
	s_waitcnt lgkmcnt(7)
	global_store_dwordx4 v[68:69], v[72:75], off nt
	v_lshl_add_u64 v[178:179], v[68:69], 0, v[186:187]
	s_waitcnt lgkmcnt(6)
	global_store_dwordx4 v[178:179], v[224:227], off nt
	v_lshl_add_u64 v[68:69], v[178:179], 0, v[186:187]
	s_waitcnt lgkmcnt(5)
	global_store_dwordx4 v[68:69], v[228:231], off nt
	v_lshl_add_u64 v[178:179], v[68:69], 0, v[186:187]
	s_waitcnt lgkmcnt(4)
	global_store_dwordx4 v[178:179], v[232:235], off nt
	v_lshl_add_u64 v[68:69], v[178:179], 0, v[186:187]
	s_waitcnt lgkmcnt(3)
	global_store_dwordx4 v[68:69], v[236:239], off nt
	v_lshl_add_u64 v[178:179], v[68:69], 0, v[186:187]
	s_waitcnt lgkmcnt(2)
	global_store_dwordx4 v[178:179], v[240:243], off nt
	v_lshl_add_u64 v[68:69], v[178:179], 0, v[186:187]
	s_waitcnt lgkmcnt(1)
	global_store_dwordx4 v[68:69], v[244:247], off nt
	v_lshl_add_u64 v[178:179], v[68:69], 0, v[186:187]
	s_waitcnt lgkmcnt(0)
	global_store_dwordx4 v[178:179], v[100:103], off nt
	v_mov_b32_e32 v64, v178
	v_mov_b32_e32 v65, v179
	v_cmp_ne_u64_e32 vcc, 0, v[66:67]
	s_mov_b64 s[16:17], 0
	s_and_saveexec_b64 s[18:19], vcc
	s_cbranch_execz .LBB0_767
	s_mov_b64 s[16:17], exec
	s_waitcnt lgkmcnt(0)
	s_barrier
